# LRU gate GEMM runs one K iteration (the zero-weight K half is skipped); S5 chunk-state GEMM units assigned to CUs 64-255; S5 matrix generation on 16 CUs beside the in-projection GEMM
# speedup vs baseline: 1.0147x; 1.0040x over previous
; __device__ __forceinline__ unsigned xb_ld(unsigned* p)              { return __hip_atomic_load(p, __ATOMIC_RELAXED, __HIP_MEMORY_SCOPE_AGENT); }
;     __device__ __forceinline__ bool next(int i, Unit& u) const {
;         const int L = i * G + c; const int per = nM * nN; if (L >= per * ngroups) return false;
;         const int g = L / per, r = L - g * per; const int pm = r / nN, pn = r - pm * nN;
;         u.pm = pm; u.pn = pn; u.aux = g; u.nt = ntk;
; __device__ __forceinline__ void xcd_barrier_complete(unsigned* bar, unsigned x, unsigned& nloc, unsigned& nx) {
;     const unsigned G = gridDim.x * gridDim.y * gridDim.z;
;     unsigned sum, cnt, mine, sp = 0u;
;     for (;;) {
;         sum = 0u; cnt = 0u; mine = 0u;
; #pragma unroll
;         for (unsigned j = 0; j < 16; ++j) { const unsigned c = xb_ld(&bar[XB_XCNT(j)]); sum += c; cnt += (c > 0u) ? 1u : 0u; mine = (j == x) ? c : mine; }
;         if (sum == G) break;
;         __builtin_amdgcn_s_sleep(1);
;         if ((++sp & 255u) == 0u) { if (xb_ld(&bar[XB_TMO])) break; if (sp > XB_SPIN_CAP) { atomicAdd(&bar[XB_TMO], 1u); break; } }
;     }
;     nloc = mine > 0u ? mine : 1u; nx = cnt > 0u ? cnt : 1u;
; }
.LBB0_20:
	s_or_b64 exec, exec, s[6:7]
	s_lshl_b32 s51, s2, 3
	s_lshl_b32 s52, s64, 3
	s_lshl_b32 s6, s2, 9
	s_lshl_b32 s70, s64, 9
	s_cmpk_lt_i32 s2, 0x100
	v_writelane_b32 v252, s6, 4
	s_cselect_b64 s[6:7], -1, 0
	s_add_u32 s94, s0, 0x2b910200
	s_addc_u32 s95, s1, 0
	s_add_u32 s96, s0, 0x2b910400
	s_addc_u32 s97, s1, 0
	s_add_u32 s90, s0, 0x2b910500
	s_addc_u32 s91, s1, 0
	s_add_u32 s88, s0, 0x2b910600
	s_addc_u32 s89, s1, 0
	s_add_u32 s92, s0, 0x2b910700
	s_addc_u32 s93, s1, 0
	s_add_u32 s74, s0, 0x2b910800
	v_writelane_b32 v252, s6, 5
	s_addc_u32 s75, s1, 0
	s_mul_i32 s65, s65, s64
	v_writelane_b32 v252, s7, 6
	s_add_u32 s6, s0, 0x2b910900
	s_addc_u32 s7, s1, 0
	v_writelane_b32 v252, s6, 7
	v_mov_b32_e32 v209, 0x358637bd
	v_mov_b32_e32 v210, 0x3c0881c4
	v_writelane_b32 v252, s7, 8
	s_add_u32 s6, s0, 0x2b910a00
	s_addc_u32 s7, s1, 0
	v_writelane_b32 v252, s6, 9
	v_mov_b32_e32 v211, 0xbab64f3b
	v_mov_b32_e32 v213, 0x260
	v_writelane_b32 v252, s7, 10
	s_add_u32 s6, s0, 0x2b910b00
	s_addc_u32 s7, s1, 0
	v_writelane_b32 v252, s6, 11
	v_mov_b32_e32 v215, 0xc000
	v_mov_b32_e32 v216, 0x7f800000
	v_writelane_b32 v252, s7, 12
	s_add_u32 s6, s0, 0x2b910c00
	s_addc_u32 s7, s1, 0
	v_writelane_b32 v252, s6, 13
	v_mov_b32_e32 v164, 0x3f317218
	v_not_b32_e32 v217, 63
	v_writelane_b32 v252, s7, 14
	s_add_u32 s6, s0, 0x2b910d00
	s_addc_u32 s7, s1, 0
	v_writelane_b32 v252, s6, 15
	v_not_b32_e32 v218, 31
	v_mov_b32_e32 v219, 0x7fc00000
	v_writelane_b32 v252, s7, 16
	s_add_u32 s6, s0, 0x2b910e00
	s_addc_u32 s7, s1, 0
	v_writelane_b32 v252, s6, 17
	v_mov_b32_e32 v221, 0xff800000
	v_mov_b32_e32 v223, 0xb000
	v_writelane_b32 v252, s7, 18
	s_add_u32 s6, s0, 0x2b910f00
	s_addc_u32 s7, s1, 0
	v_writelane_b32 v252, s6, 19
	s_movk_i32 s72, 0x208
	s_mov_b32 s33, 0x7e07e07f
	v_writelane_b32 v252, s7, 20
	s_add_u32 s6, s0, 0x2b911000
	s_addc_u32 s7, s1, 0
	s_add_u32 s10, s0, 0x2b911100
	v_writelane_b32 v252, s6, 21
	s_addc_u32 s11, s1, 0
	s_movk_i32 s63, 0x1800
	v_writelane_b32 v252, s7, 22
	s_add_u32 s6, s0, 0x2b911200
	s_addc_u32 s7, s1, 0
	s_add_u32 s8, s0, 0x2b911300
	s_addc_u32 s9, s1, 0
	s_cmp_eq_u32 s3, 15
	s_cselect_b64 s[14:15], -1, 0
	v_writelane_b32 v252, s14, 23
	s_cmp_eq_u32 s3, 14
	s_movk_i32 s42, 0x40ff
	v_writelane_b32 v252, s15, 24
	s_cselect_b64 s[14:15], -1, 0
	v_writelane_b32 v252, s14, 25
	s_cmp_eq_u32 s3, 13
	s_movk_i32 s76, 0x5ff
	v_writelane_b32 v252, s15, 26
	s_cselect_b64 s[14:15], -1, 0
	v_writelane_b32 v252, s14, 27
	s_cmp_eq_u32 s3, 12
	s_movk_i32 s73, 0x2000
	v_writelane_b32 v252, s15, 28
	s_cselect_b64 s[14:15], -1, 0
	v_writelane_b32 v252, s14, 29
	s_cmp_eq_u32 s3, 11
	s_movk_i32 s50, 0x6000
	v_writelane_b32 v252, s15, 30
	s_cselect_b64 s[14:15], -1, 0
	v_writelane_b32 v252, s14, 31
	s_cmp_eq_u32 s3, 10
	s_mov_b32 s53, 0x8000
	v_writelane_b32 v252, s15, 32
	s_cselect_b64 s[14:15], -1, 0
	v_writelane_b32 v252, s14, 33
	s_cmp_eq_u32 s3, 9
	s_mov_b32 s54, 0xa000
	v_writelane_b32 v252, s15, 34
	s_cselect_b64 s[14:15], -1, 0
	v_writelane_b32 v252, s14, 35
	s_cmp_eq_u32 s3, 8
	s_mov_b32 s55, 0xc000
	v_writelane_b32 v252, s15, 36
	s_cselect_b64 s[14:15], -1, 0
	v_writelane_b32 v252, s14, 37
	s_cmp_eq_u32 s3, 7
	s_mov_b32 s56, 0xe000
	v_writelane_b32 v252, s15, 38
	s_cselect_b64 s[14:15], -1, 0
	v_writelane_b32 v252, s14, 39
	s_cmp_eq_u32 s3, 6
	s_mov_b32 s57, 0x16000
	v_writelane_b32 v252, s15, 40
	s_cselect_b64 s[14:15], -1, 0
	v_writelane_b32 v252, s14, 41
	s_cmp_eq_u32 s3, 5
	s_movk_i32 s77, 0x80
	v_writelane_b32 v252, s15, 42
	s_cselect_b64 s[14:15], -1, 0
	v_writelane_b32 v252, s14, 43
	s_cmp_eq_u32 s3, 4
	s_mov_b32 s78, 0x3fb8aa3b
	v_writelane_b32 v252, s15, 44
	s_cselect_b64 s[14:15], -1, 0
	v_writelane_b32 v252, s14, 45
	s_cmp_eq_u32 s3, 3
	s_mov_b32 s79, 0xc2ce8ed0
	v_writelane_b32 v252, s15, 46
	s_cselect_b64 s[14:15], -1, 0
	v_writelane_b32 v252, s14, 47
	s_cmp_eq_u32 s3, 2
	s_mov_b32 s80, 0x42b17218
	v_writelane_b32 v252, s15, 48
	s_cselect_b64 s[14:15], -1, 0
	v_writelane_b32 v252, s14, 49
	s_cmp_eq_u32 s3, 1
	s_brev_b32 s81, 18
	v_writelane_b32 v252, s15, 50
	s_cselect_b64 s[14:15], -1, 0
	v_writelane_b32 v252, s14, 51
	s_cmp_eq_u32 s3, 0
	s_brev_b32 s82, 1
	v_writelane_b32 v252, s15, 52
	s_cselect_b64 s[14:15], -1, 0
	s_lshl_b32 s3, s12, 2
	s_add_u32 s3, s4, s3
	s_addc_u32 s4, s5, 0
	v_writelane_b32 v252, s14, 53
	s_add_u32 s12, s3, 0x1400
	s_addc_u32 s13, s4, 0
	v_writelane_b32 v252, s15, 54
	v_writelane_b32 v252, s12, 55
	s_movk_i32 s83, 0x1f8
	s_movk_i32 s84, 0x2800
	v_writelane_b32 v252, s13, 56
	s_add_u32 s12, s3, 0x2400
	s_addc_u32 s13, s4, 0
	v_writelane_b32 v252, s12, 57
	s_add_u32 s4, s0, 0x2b913400
	s_addc_u32 s5, s1, 0
	v_writelane_b32 v252, s13, 58
	v_writelane_b32 v252, s4, 59
	s_add_u32 s0, s0, 0x2b913500
	s_addc_u32 s1, s1, 0
	v_writelane_b32 v252, s5, 60
	v_writelane_b32 v252, s0, 61
	s_cmpk_lt_i32 s2, 0xc30
	s_movk_i32 s85, 0x500
	v_writelane_b32 v252, s1, 62
	s_cselect_b64 s[0:1], -1, 0
	v_writelane_b32 v252, s0, 63
	s_ashr_i32 s3, s2, 31
	s_mov_b32 s86, 0xf800000
	v_writelane_b32 v253, s1, 0
	s_lshr_b32 s0, s3, 29
	s_add_i32 s1, s2, s0
	s_ashr_i32 s0, s1, 3
	s_and_b32 s1, s1, -8
	s_sub_i32 s4, s2, s1
	s_cmpk_lt_i32 s2, 0x820
	s_cselect_b64 s[12:13], -1, 0
	v_writelane_b32 v253, s12, 1
	s_cmpk_lt_i32 s2, 0x208
	s_mul_hi_i32 s1, s2, 0x7e07e07f
	v_writelane_b32 v253, s13, 2
	s_cselect_b64 s[12:13], -1, 0
	s_lshr_b32 s5, s1, 31
	s_ashr_i32 s1, s1, 5
	s_add_i32 s14, s1, s5
	s_mul_i32 s1, s14, 0xffffffbf
	v_writelane_b32 v253, s12, 3
	s_add_i32 s16, s1, s2
	s_ashr_i32 s17, s16, 31
	v_writelane_b32 v253, s13, 4
	s_mov_b32 s12, s16
	v_writelane_b32 v253, s12, 5
	s_ashr_i32 s15, s14, 31
	s_sub_u32 vcc_lo, 0xff, s2
;     __device__ __forceinline__ bool next(int i, Unit& u) const {
;         const int L = i * G + c; const int per = nM * nN; if (L >= per * ngroups) return false;
;         const int g = L / per, r = L - g * per; const int pm = r / nN, pn = r - pm * nN;
;         u.pm = pm; u.pn = pn; u.aux = g; u.nt = ntk;
	s_mul_hi_i32 s1, vcc_lo, 0x55555556
	v_writelane_b32 v253, s13, 6
	s_lshl_b64 s[12:13], s[16:17], 19
	v_writelane_b32 v253, s12, 7
	s_mov_b32 s87, 0xff800000
	s_mov_b64 s[36:37], 0x10000
	v_writelane_b32 v253, s13, 8
	s_lshl_b64 s[12:13], s[14:15], 8
	v_writelane_b32 v253, s12, 9
	s_mov_b64 s[38:39], 0x28000
	s_mov_b32 s62, 0x3b808081
	v_writelane_b32 v253, s13, 10
	s_mov_b32 s12, s14
	v_writelane_b32 v253, s12, 11
	s_mov_b32 s28, s69
	s_nop 0
	v_writelane_b32 v253, s13, 12
	s_lshl_b64 s[12:13], s[14:15], 17
	v_writelane_b32 v253, s12, 13
	s_cmpk_lt_i32 vcc_lo, 0xc0
	s_nop 0
	v_writelane_b32 v253, s13, 14
	s_cselect_b64 s[12:13], -1, 0
	s_lshr_b32 s5, s1, 31
	s_add_i32 s14, s1, s5
	v_writelane_b32 v253, s12, 15
	s_mul_i32 s1, s14, -3
	s_add_i32 s1, s1, vcc_lo
	v_writelane_b32 v253, s13, 16
	v_writelane_b32 v253, s1, 17
	s_not_b32 s1, s2
	s_add_i32 s1, s64, s1
	v_writelane_b32 v253, s1, 18
	s_mov_b32 s12, s14
	s_ashr_i32 s15, s14, 31
	v_writelane_b32 v253, s12, 19
	s_mul_hi_i32 s1, s2, 0x2aaaaaab
	s_nop 0
	v_writelane_b32 v253, s13, 20
	s_lshl_b64 s[12:13], s[14:15], 17
	v_writelane_b32 v253, s12, 21
	s_cmpk_lt_i32 s2, 0x180
	s_nop 0
	v_writelane_b32 v253, s13, 22
	s_cselect_b64 s[12:13], -1, 0
	v_writelane_b32 v253, s12, 23
	s_lshr_b32 s5, s1, 31
	s_add_i32 s1, s1, s5
	v_writelane_b32 v253, s13, 24
	v_writelane_b32 v253, s1, 25
	s_mul_i32 s1, s1, -6
	s_add_i32 s1, s1, s2
	s_lshr_b32 s5, s1, 31
	s_add_i32 s5, s1, s5
	s_and_b32 s12, s5, -2
	s_sub_i32 s1, s1, s12
	v_writelane_b32 v253, s1, 26
	s_ashr_i32 s1, s5, 1
	s_cmpk_lt_i32 s2, 0x104
	v_writelane_b32 v253, s1, 27
	s_cselect_b64 s[12:13], -1, 0
	v_writelane_b32 v253, s12, 28
	s_lshl_b32 s1, s4, 5
	s_or_b32 s1, s1, 4
	v_writelane_b32 v253, s13, 29
	s_lshl_b32 s5, s4, 6
	s_lshl_b64 s[12:13], s[2:3], 17
	v_writelane_b32 v253, s12, 30
	s_cmpk_lt_i32 s2, 0x200
	s_nop 0
	v_writelane_b32 v253, s13, 31
	s_cselect_b64 s[12:13], -1, 0
	v_writelane_b32 v253, s12, 32
	s_cmpk_gt_i32 s2, 0x1ff
	s_nop 0
	v_writelane_b32 v253, s13, 33
	s_cselect_b64 s[12:13], -1, 0
	s_add_i32 s3, s2, 0xfffffe00
	v_writelane_b32 v253, s12, 34
	s_cmp_lt_u32 s3, 32
	s_nop 0
	v_writelane_b32 v253, s13, 35
	s_cselect_b64 s[12:13], -1, 0
	v_writelane_b32 v253, s12, 36
	s_nop 1
	v_writelane_b32 v253, s13, 37
	s_bfe_u32 s12, s2, 0x30002
	v_writelane_b32 v253, s12, 38
	s_lshl_b32 s12, s12, 2
	s_sub_i32 s12, s3, s12
	v_writelane_b32 v253, s12, 39
	s_cmpk_lt_i32 s2, 0xb2c
	s_mul_i32 s12, s4, 0x165
	s_cselect_b64 s[14:15], -1, 0
	s_add_i32 s12, s12, 4
	v_writelane_b32 v253, s14, 40
	s_cmpk_lt_u32 s3, 0x58
	s_nop 0
	v_writelane_b32 v253, s15, 41
	s_cselect_b64 s[14:15], -1, 0
	s_and_b32 s13, s2, 0xff
	s_mulk_i32 s13, 0x75
	v_writelane_b32 v253, s14, 42
	s_lshr_b32 s13, s13, 8
	s_nop 0
	v_writelane_b32 v253, s15, 43
	s_sub_i32 s14, s2, s13
	s_bfe_u32 s14, s14, 0x70001
	s_add_i32 s14, s14, s13
	s_bfe_u32 s13, s14, 0x50003
	v_writelane_b32 v253, s13, 44
	s_mul_i32 s13, s13, -11
	s_add_i32 s3, s13, s3
	v_writelane_b32 v253, s3, 45
	s_cmp_lt_i32 s4, 4
	s_mul_i32 s3, s4, 33
	s_cselect_b32 s3, s3, s1
	s_mul_i32 s1, s4, 0x166
	s_cselect_b32 s12, s1, s12
	s_abs_i32 s1, s64
	v_cvt_f32_u32_e32 v0, s1
	s_sub_i32 s13, 0, s1
	s_ashr_i32 s15, s64, 31
	v_rcp_iflag_f32_e32 v0, v0
	s_nop 0
	v_mul_f32_e32 v0, 0x4f7ffffe, v0
	v_cvt_u32_f32_e32 v0, v0
	s_nop 0
	v_readfirstlane_b32 s14, v0
	s_mul_i32 s13, s13, s14
	s_mul_hi_u32 s13, s14, s13
	s_add_i32 s14, s14, s13
	s_lshr_b32 s13, s14, 23
	s_mul_i32 s14, s13, s1
	s_sub_i32 s14, 0x200, s14
	s_add_i32 s16, s13, 1
	s_sub_i32 s17, s14, s1
	s_cmp_ge_u32 s14, s1
	s_cselect_b32 s13, s16, s13
	s_cselect_b32 s14, s17, s14
	s_add_i32 s16, s13, 1
	s_cmp_ge_u32 s14, s1
	s_cselect_b32 s1, s16, s13
	s_xor_b32 s1, s1, s15
	s_sub_i32 s1, s1, s15
	s_cmp_lt_i32 s4, 0
	s_movk_i32 s13, 0x187
	s_cselect_b32 s13, s13, 0x186
	s_mul_i32 s13, s4, s13
	s_mulk_i32 s4, 0x41
	s_cselect_b32 s4, s4, s5
	s_add_i32 s13, s13, s0
	s_mul_hi_i32 s5, s13, 0x2aaaaaab
	s_lshr_b32 s14, s5, 31
	s_ashr_i32 s5, s5, 6
	s_add_i32 s5, s5, s14
	s_mul_i32 s14, s5, 0x180
	s_add_i32 s3, s3, s0
	s_sub_i32 s13, s13, s14
	s_ashr_i32 s14, s3, 31
	s_lshr_b32 s14, s14, 27
	s_add_i32 s14, s3, s14
	s_and_b32 s15, s14, 0xffffffe0
	s_add_i32 s4, s4, s0
	s_sub_i32 s3, s3, s15
	s_ashr_i32 s15, s4, 31
	s_lshr_b32 s15, s15, 26
	s_add_i32 s15, s4, s15
	s_add_i32 s12, s12, s0
	s_and_b32 s16, s15, 0xffffffc0
	s_mul_hi_i32 s0, s12, 0x2e8ba2e9
	s_sub_i32 s16, s4, s16
	s_lshr_b32 s4, s0, 31
	s_ashr_i32 s0, s0, 6
	s_add_i32 s0, s0, s4
	s_mul_i32 s4, s0, 0x160
	s_sub_i32 s17, s12, s4
	s_lshl_b32 s12, s5, 3
	s_sub_i32 s4, 0x41, s12
	s_min_u32 s18, s4, 8
	s_ashr_i32 s4, s14, 5
	s_lshl_b32 s14, s4, 3
	s_sub_i32 s4, 0x41, s14
	s_min_u32 s19, s4, 8
	s_ashr_i32 s4, s15, 6
	s_lshl_b32 s15, s4, 3
	s_sub_i32 s4, 64, s15
	s_min_i32 s20, s4, 8
	s_bfe_i32 s4, s16, 0x80000
	v_cvt_f32_ubyte0_e32 v1, s18
	s_bfe_u32 s4, s4, 0x3000c
	v_cvt_f32_i32_e32 v0, s13
	v_rcp_iflag_f32_e32 v2, v1
	s_add_i32 s4, s16, s4
	s_bfe_i32 s5, s4, 0x80000
	s_and_b32 s4, s4, 0xf8
	s_sub_i32 s4, s16, s4
	s_sext_i32_i8 s4, s4
	v_mul_f32_e32 v2, v0, v2
	s_sext_i32_i16 s5, s5
	s_add_i32 s4, s15, s4
	v_trunc_f32_e32 v2, v2
	v_writelane_b32 v253, s4, 46
	s_ashr_i32 s4, s5, 3
	s_lshl_b32 s21, s0, 3
	v_fma_f32 v0, -v2, v1, v0
	v_writelane_b32 v253, s4, 47
	s_sub_i32 s0, 0x41, s21
	v_cmp_ge_f32_e64 s[4:5], |v0|, v1
	v_cvt_i32_f32_e32 v0, v2
	s_min_u32 s22, s0, 8
	s_ashr_i32 s0, s13, 30
	s_or_b32 s0, s0, 1
	s_and_b64 s[4:5], s[4:5], exec
	s_cselect_b32 s0, s0, 0
	v_readfirstlane_b32 s4, v0
	s_add_i32 s0, s4, s0
	s_mul_i32 s4, s0, s18
	s_sub_i32 s4, s13, s4
	s_sext_i32_i16 s4, s4
	s_add_i32 s26, s12, s4
; #define LAS __attribute__((address_space(3)))
; __global__ void __launch_bounds__(512, 2) mega_fwd(Params P) {
;     extern __shared__ __attribute__((aligned(16))) unsigned char lds_raw[];
;     LAS unsigned char* lds = (LAS unsigned char*)lds_raw;
;     cg::grid_group grid = cg::this_grid();
;     const int G = gridDim.x, c = blockIdx.x;
;     volatile LAS unsigned* bst = (volatile LAS unsigned*)(lds + 131072 + 512);
;     if (threadIdx.x < 2) bst[threadIdx.x] = 0u;
;     if (c == 0) for (int i = threadIdx.x; i < XCD_BAR_WORDS; i += 512) __hip_atomic_store((unsigned*)(P.ws + WS_BAR) + i, 0u, __ATOMIC_RELAXED, __HIP_MEMORY_SCOPE_AGENT);
;     grid.sync();
;     const XcdBarrier xbar = xcd_barrier_post((unsigned*)(P.ws + WS_BAR), bst);
	v_cvt_f32_ubyte0_e32 v1, s19
	s_bfe_i64 s[4:5], s[0:1], 0x100000
	v_cvt_f32_i32_e32 v0, s3
	v_rcp_iflag_f32_e32 v2, v1
	s_lshl_b64 s[4:5], s[4:5], 20
	v_writelane_b32 v253, s4, 48
	s_ashr_i32 s27, s26, 31
	v_mul_f32_e32 v2, v0, v2
	v_writelane_b32 v253, s5, 49
	s_ashr_i32 s4, s3, 30
	s_or_b32 s12, s4, 1
	s_mov_b32 s4, s26
	v_writelane_b32 v253, s4, 50
	v_trunc_f32_e32 v2, v2
	v_fma_f32 v0, -v2, v1, v0
	v_writelane_b32 v253, s5, 51
	s_lshl_b64 s[4:5], s[26:27], 20
	v_writelane_b32 v253, s4, 52
	s_sext_i32_i16 s0, s0
	s_movk_i32 s27, 0xefc0
	v_writelane_b32 v253, s5, 53
	v_cmp_ge_f32_e64 s[4:5], |v0|, v1
	v_cvt_i32_f32_e32 v0, v2
	s_and_b64 s[4:5], s[4:5], exec
	s_cselect_b32 s4, s12, 0
	v_cvt_f32_ubyte0_e32 v1, s22
	v_readfirstlane_b32 s5, v0
	s_add_i32 s4, s5, s4
	s_mul_i32 s5, s4, s19
	s_sub_i32 s3, s3, s5
	s_sext_i32_i8 s3, s3
	s_add_i32 s3, s14, s3
	s_bfe_i64 s[12:13], s[4:5], 0x80000
	v_writelane_b32 v253, s3, 54
	s_lshl_b64 s[12:13], s[12:13], 19
	v_writelane_b32 v253, s12, 55
	s_cmp_gt_i32 s1, 0
	s_mul_i32 s3, s64, s1
	v_writelane_b32 v253, s13, 56
	s_cselect_b64 s[12:13], -1, 0
	v_writelane_b32 v253, s12, 57
	s_cmp_lt_i32 s1, 1
	s_mul_i32 s3, s3, -3
	v_writelane_b32 v253, s13, 58
	s_cselect_b64 s[12:13], -1, 0
	s_add_i32 s3, s3, s2
	v_writelane_b32 v253, s12, 59
	s_cmpk_lt_i32 s3, 0x60
	s_mul_hi_i32 s5, s3, 0x2aaaaaab
	v_writelane_b32 v253, s13, 60
	s_cselect_b64 s[12:13], -1, 0
	v_writelane_b32 v253, s12, 61
	v_rcp_iflag_f32_e32 v2, v1
	s_mul_i32 s1, s1, 3
	v_writelane_b32 v253, s13, 62
	s_lshr_b32 s12, s5, 31
	s_ashr_i32 s5, s5, 1
	s_add_i32 s5, s5, s12
	v_writelane_b32 v253, s5, 63
	s_mul_i32 s5, s5, -12
	s_add_i32 s3, s5, s3
	s_abs_i32 s5, s20
	v_cvt_f32_u32_e32 v0, s5
	s_sub_i32 s12, 0, s5
	s_mov_b32 s26, 0x437f0000
	v_rcp_iflag_f32_e32 v0, v0
	s_nop 0
	v_mul_f32_e32 v0, 0x4f7ffffe, v0
	v_cvt_u32_f32_e32 v0, v0
	s_nop 0
	v_readfirstlane_b32 s13, v0
	s_mul_i32 s12, s12, s13
	s_mul_hi_u32 s12, s13, s12
	s_add_i32 s13, s13, s12
	s_abs_i32 s12, s16
	s_mul_hi_u32 s14, s12, s13
	s_mul_i32 s13, s14, s5
	s_sub_i32 s18, s12, s13
	s_ashr_i32 s12, s3, 31
	s_lshr_b32 s12, s12, 30
	s_add_i32 s12, s3, s12
	s_ashr_i32 s13, s12, 2
	s_and_b32 s12, s12, -4
	s_sub_i32 s12, s3, s12
	s_lshl_b32 s3, s12, 2
	s_add_i32 s3, s3, 4
	v_writelane_b32 v254, s13, 0
	s_or_b32 s3, s3, s13
	s_ashr_i32 s13, s12, 31
	v_writelane_b32 v254, s3, 1
	s_lshl_b64 s[12:13], s[12:13], 9
	v_writelane_b32 v254, s12, 2
	s_xor_b32 s3, s16, s20
	s_ashr_i32 s3, s3, 31
	v_writelane_b32 v254, s13, 3
	s_add_i32 s12, s14, 1
	s_sub_i32 s13, s18, s5
	s_cmp_ge_u32 s18, s5
	s_cselect_b32 s12, s12, s14
	s_cselect_b32 s13, s13, s18
	s_add_i32 s14, s12, 1
	v_cvt_f32_i32_e32 v0, s17
	s_cmp_ge_u32 s13, s5
	s_cselect_b32 s5, s14, s12
	s_xor_b32 s5, s5, s3
	s_sub_i32 s3, s5, s3
	v_mul_f32_e32 v2, v0, v2
	v_writelane_b32 v254, s3, 4
	s_mul_i32 s3, s3, s20
	v_trunc_f32_e32 v2, v2
	s_sub_i32 s3, s16, s3
	v_fma_f32 v0, -v2, v1, v0
	s_add_i32 s3, s15, s3
	v_cmp_ge_f32_e64 s[12:13], |v0|, v1
	v_cvt_i32_f32_e32 v0, v2
	v_writelane_b32 v254, s3, 5
	s_ashr_i32 s3, s17, 30
	s_or_b32 s3, s3, 1
	s_and_b64 s[12:13], s[12:13], exec
	v_writelane_b32 v254, s0, 6
	s_sext_i32_i8 s0, s4
	v_writelane_b32 v254, s0, 7
	s_cselect_b32 s0, s3, 0
	v_readfirstlane_b32 s3, v0
	s_add_i32 s0, s3, s0
	s_mul_i32 s3, s0, s22
	s_sub_i32 s3, s17, s3
	v_writelane_b32 v254, s1, 8
	s_sext_i32_i16 s1, s3
	s_add_i32 s4, s21, s1
	s_sext_i32_i16 s1, s0
	v_writelane_b32 v254, s1, 9
	s_bfe_i64 s[0:1], s[0:1], 0x100000
	s_lshl_b64 s[0:1], s[0:1], 20
	v_writelane_b32 v254, s0, 10
	s_load_dword s5, s[24:25], 0x100
	s_ashr_i32 s71, s70, 31
	v_writelane_b32 v254, s1, 11
	s_add_i32 s0, s51, 0xffffc000
	v_writelane_b32 v254, s0, 12
	s_lshl_b32 s0, s2, 12
	v_writelane_b32 v254, s0, 13
	s_lshl_b32 s0, s64, 12
	v_writelane_b32 v254, s0, 14
	s_lshl_b32 s0, s2, 6
	v_writelane_b32 v254, s0, 15
	s_add_i32 s0, 0, 0x6200
	v_writelane_b32 v254, s0, 16
	s_add_i32 s0, 0, 0x4200
	v_writelane_b32 v254, s0, 17
	s_add_i32 s0, 0, 0x20200
	v_writelane_b32 v254, s0, 18
	s_add_i32 s0, 0, 0x20204
	v_writelane_b32 v254, s0, 19
	s_add_i32 s0, 0, 0x11800
	v_writelane_b32 v254, s0, 20
	s_add_i32 s0, 0, 0x15634
	v_writelane_b32 v254, s0, 21
	s_mov_b32 s0, s4
	s_waitcnt lgkmcnt(0)
	s_mul_i32 s65, s65, s5
	s_ashr_i32 s5, s4, 31
	v_writelane_b32 v254, s0, 22
	s_lshl_b32 s35, s64, 6
	v_mov_b32_e32 v1, 0
	v_writelane_b32 v254, s1, 23
	s_lshl_b64 s[0:1], s[4:5], 20
	s_load_dwordx2 s[4:5], s[24:25], 0xf0
	v_writelane_b32 v254, s0, 24
	s_mov_b32 s3, 0x21000000
	s_mov_b64 s[20:21], 0x800
	v_writelane_b32 v254, s1, 25
	s_lshl_b64 s[0:1], s[70:71], 1
	v_writelane_b32 v254, s0, 26
	s_movk_i32 s71, 0x1ff
	s_mov_b64 s[22:23], 0x80
	v_writelane_b32 v254, s1, 27
	s_waitcnt lgkmcnt(0)
	v_writelane_b32 v254, s4, 28
	s_mov_b64 s[0:1], -1
	s_mov_b64 s[12:13], 0x14000
	v_writelane_b32 v254, s5, 29
	v_writelane_b32 v254, s24, 30
	s_load_dwordx4 s[16:19], s[24:25], 0x0
	s_nop 0
	v_writelane_b32 v254, s25, 31
	s_mov_b32 s24, 0
	s_waitcnt lgkmcnt(0)
	v_writelane_b32 v254, s16, 32
	s_nop 1
	v_writelane_b32 v254, s17, 33
	v_writelane_b32 v254, s18, 34
	v_writelane_b32 v254, s19, 35
	v_writelane_b32 v254, s94, 36
	s_nop 1
	v_writelane_b32 v254, s95, 37
	v_writelane_b32 v254, s96, 38
	s_nop 1
	v_writelane_b32 v254, s97, 39
	v_writelane_b32 v254, s90, 40
	s_nop 1
	v_writelane_b32 v254, s91, 41
	v_writelane_b32 v254, s88, 42
	s_nop 1
	v_writelane_b32 v254, s89, 43
	v_writelane_b32 v254, s92, 44
	s_nop 1
	v_writelane_b32 v254, s93, 45
	v_writelane_b32 v254, s74, 46
	s_nop 1
	v_writelane_b32 v254, s75, 47
	v_writelane_b32 v254, s51, 48
	v_writelane_b32 v254, s35, 49
	v_writelane_b32 v254, s52, 50
	s_branch .LBB0_23

; template <class Epi, class Sched>
; __device__ __forceinline__ void gemm_phase(LAS unsigned char* lds, const int lda, const int ldb, const Sched& S, const Epi& E) {
;     ...
;         const int nt = cur.nt;
; #pragma unroll 1
;         for (int t = 0; t < nt; t += 2) {
;             const bool last = (t == nt - 2);
;             const char* a1 = cA + (size_t)(t + 1) * kstep;
;             const char* a2 = last ? nA : cA + (size_t)(t + 2) * kstep; const char* b2 = last ? nB : cB + (size_t)(t + 2) * kstep;
;     ...
;         for (int a = 0; a < 2; ++a)
; #pragma unroll
;             for (int b = 0; b < 2; ++b)
; #pragma unroll
;                 for (int m = 0; m < 4; ++m)
; #pragma unroll
;                     for (int n = 0; n < 2; ++n) acc[a][b][m][n] = (f32x4){0.f, 0.f, 0.f, 0.f};
;         cur = nxt; cA = nA; cB = nB; ++ui;
.LBB0_487:
	v_mov_b32_e32 v2, 0
	s_mov_b32 s25, 0
	s_mov_b64 s[46:47], 0
	s_mov_b64 s[48:49], -1
	v_mov_b32_e32 v3, v2
	v_mov_b32_e32 v4, v2
	v_mov_b32_e32 v5, v2
	s_waitcnt vmcnt(0)
	v_mov_b32_e32 v66, v2
	v_mov_b32_e32 v67, v2
	v_mov_b32_e32 v68, v2
	v_mov_b32_e32 v69, v2
	v_mov_b32_e32 v10, v2
	v_mov_b32_e32 v11, v2
	v_mov_b32_e32 v12, v2
	v_mov_b32_e32 v13, v2
	v_mov_b32_e32 v74, v2
	v_mov_b32_e32 v75, v2
	v_mov_b32_e32 v76, v2
	v_mov_b32_e32 v77, v2
	v_mov_b32_e32 v18, v2
	v_mov_b32_e32 v19, v2
	v_mov_b32_e32 v20, v2
	v_mov_b32_e32 v21, v2
	v_mov_b32_e32 v94, v2
	v_mov_b32_e32 v95, v2
	v_mov_b32_e32 v96, v2
	v_mov_b32_e32 v97, v2
	v_mov_b32_e32 v26, v2
	v_mov_b32_e32 v27, v2
	v_mov_b32_e32 v28, v2
	v_mov_b32_e32 v29, v2
	v_mov_b32_e32 v102, v2
	v_mov_b32_e32 v103, v2
	v_mov_b32_e32 v104, v2
	v_mov_b32_e32 v105, v2
	v_mov_b32_e32 v6, v2
	v_mov_b32_e32 v7, v2
	v_mov_b32_e32 v8, v2
	v_mov_b32_e32 v9, v2
	v_mov_b32_e32 v70, v2
	v_mov_b32_e32 v71, v2
	v_mov_b32_e32 v72, v2
	v_mov_b32_e32 v73, v2
	v_mov_b32_e32 v14, v2
	v_mov_b32_e32 v15, v2
	v_mov_b32_e32 v16, v2
	v_mov_b32_e32 v17, v2
	v_mov_b32_e32 v78, v2
	v_mov_b32_e32 v79, v2
	v_mov_b32_e32 v80, v2
	v_mov_b32_e32 v81, v2
	v_mov_b32_e32 v22, v2
	v_mov_b32_e32 v23, v2
	v_mov_b32_e32 v24, v2
	v_mov_b32_e32 v25, v2
	v_mov_b32_e32 v98, v2
	v_mov_b32_e32 v99, v2
	v_mov_b32_e32 v100, v2
	v_mov_b32_e32 v101, v2
	v_mov_b32_e32 v30, v2
	v_mov_b32_e32 v31, v2
	v_mov_b32_e32 v32, v2
	v_mov_b32_e32 v33, v2
	v_mov_b32_e32 v106, v2
	v_mov_b32_e32 v107, v2
	v_mov_b32_e32 v108, v2
	v_mov_b32_e32 v109, v2
	v_mov_b32_e32 v34, v2
	v_mov_b32_e32 v35, v2
	v_mov_b32_e32 v36, v2
	v_mov_b32_e32 v37, v2
	v_mov_b32_e32 v110, v2
	v_mov_b32_e32 v111, v2
	v_mov_b32_e32 v112, v2
	v_mov_b32_e32 v113, v2
	v_mov_b32_e32 v42, v2
	v_mov_b32_e32 v43, v2
	v_mov_b32_e32 v44, v2
	v_mov_b32_e32 v45, v2
	v_mov_b32_e32 v118, v2
	v_mov_b32_e32 v119, v2
	v_mov_b32_e32 v120, v2
	v_mov_b32_e32 v121, v2
	v_mov_b32_e32 v50, v2
	v_mov_b32_e32 v51, v2
	v_mov_b32_e32 v52, v2
	v_mov_b32_e32 v53, v2
	v_mov_b32_e32 v126, v2
	v_mov_b32_e32 v127, v2
	v_mov_b32_e32 v128, v2
	v_mov_b32_e32 v129, v2
	v_mov_b32_e32 v58, v2
	v_mov_b32_e32 v59, v2
	v_mov_b32_e32 v60, v2
	v_mov_b32_e32 v61, v2
	v_mov_b32_e32 v134, v2
	v_mov_b32_e32 v135, v2
	v_mov_b32_e32 v136, v2
	v_mov_b32_e32 v137, v2
	v_mov_b32_e32 v38, v2
	v_mov_b32_e32 v39, v2
	v_mov_b32_e32 v40, v2
	v_mov_b32_e32 v41, v2
	v_mov_b32_e32 v114, v2
	v_mov_b32_e32 v115, v2
	v_mov_b32_e32 v116, v2
	v_mov_b32_e32 v117, v2
	v_mov_b32_e32 v46, v2
	v_mov_b32_e32 v47, v2
	v_mov_b32_e32 v48, v2
	v_mov_b32_e32 v49, v2
	v_mov_b32_e32 v122, v2
	v_mov_b32_e32 v123, v2
	v_mov_b32_e32 v124, v2
	v_mov_b32_e32 v125, v2
	v_mov_b32_e32 v54, v2
	v_mov_b32_e32 v55, v2
	v_mov_b32_e32 v56, v2
	v_mov_b32_e32 v57, v2
	v_mov_b32_e32 v130, v2
	v_mov_b32_e32 v131, v2
	v_mov_b32_e32 v132, v2
	v_mov_b32_e32 v133, v2
	v_mov_b32_e32 v62, v2
	v_mov_b32_e32 v63, v2
	v_mov_b32_e32 v64, v2
	v_mov_b32_e32 v65, v2
	v_mov_b32_e32 v138, v2
	v_mov_b32_e32 v139, v2
	v_mov_b32_e32 v140, v2
	v_mov_b32_e32 v141, v2
